# GEMM tile headers: the 128 accumulator zero moves per tile written as 64 v_mov_b64 (21 GEMM instances)
# baseline (speedup 1.0000x reference)
.LBB0_153:
	s_ashr_i32 s29, s28, 31
	s_lshl_b64 s[30:31], s[28:29], 19
	s_add_u32 s30, s96, s30
	s_addc_u32 s31, s97, s31
	s_and_b64 s[34:35], s[0:1], exec
	s_cselect_b32 s5, s31, s11
	s_cselect_b32 s7, s30, s10
	s_ashr_i32 s27, s26, 31
	s_lshl_b64 s[34:35], s[26:27], 19
	s_add_u32 s34, s8, s34
	s_addc_u32 s35, s9, s35
	s_and_b64 s[36:37], s[0:1], exec
	s_cselect_b32 s27, s35, s13
	s_cselect_b32 s29, s34, s12
	s_add_u32 s10, s10, 0x40080
	s_addc_u32 s11, s11, 0
	s_add_u32 s38, s12, 0x100
	v_mov_b32_e32 v0, 0
	s_addc_u32 s39, s13, 0
	s_mov_b32 s54, -2
	v_mov_b32_e32 v1, 0
	v_mov_b64_e32 v[2:3], 0
	v_mov_b64_e32 v[4:5], 0
	v_mov_b64_e32 v[6:7], 0
	v_mov_b64_e32 v[8:9], 0
	v_mov_b64_e32 v[10:11], 0
	v_mov_b64_e32 v[12:13], 0
	v_mov_b64_e32 v[14:15], 0
	v_mov_b64_e32 v[16:17], 0
	v_mov_b64_e32 v[18:19], 0
	v_mov_b64_e32 v[20:21], 0
	v_mov_b64_e32 v[22:23], 0
	v_mov_b64_e32 v[24:25], 0
	v_mov_b64_e32 v[26:27], 0
	v_mov_b64_e32 v[28:29], 0
	v_mov_b64_e32 v[30:31], 0
	v_mov_b64_e32 v[32:33], 0
	v_mov_b64_e32 v[34:35], 0
	v_mov_b64_e32 v[36:37], 0
	v_mov_b64_e32 v[38:39], 0
	v_mov_b64_e32 v[40:41], 0
	v_mov_b64_e32 v[42:43], 0
	v_mov_b64_e32 v[44:45], 0
	v_mov_b64_e32 v[46:47], 0
	v_mov_b64_e32 v[48:49], 0
	v_mov_b64_e32 v[50:51], 0
	v_mov_b64_e32 v[52:53], 0
	v_mov_b64_e32 v[54:55], 0
	v_mov_b64_e32 v[56:57], 0
	v_mov_b64_e32 v[58:59], 0
	v_mov_b64_e32 v[60:61], 0
	v_mov_b64_e32 v[62:63], 0
	v_mov_b64_e32 v[64:65], 0
	v_mov_b64_e32 v[66:67], 0
	v_mov_b64_e32 v[68:69], 0
	v_mov_b64_e32 v[70:71], 0
	v_mov_b64_e32 v[72:73], 0
	v_mov_b64_e32 v[74:75], 0
	v_mov_b64_e32 v[76:77], 0
	v_mov_b64_e32 v[78:79], 0
	v_mov_b64_e32 v[80:81], 0
	v_mov_b64_e32 v[82:83], 0
	v_mov_b64_e32 v[84:85], 0
	v_mov_b64_e32 v[86:87], 0
	v_mov_b64_e32 v[88:89], 0
	v_mov_b64_e32 v[90:91], 0
	v_mov_b64_e32 v[92:93], 0
	v_mov_b64_e32 v[94:95], 0
	v_mov_b64_e32 v[96:97], 0
	v_mov_b64_e32 v[98:99], 0
	v_mov_b64_e32 v[100:101], 0
	v_mov_b64_e32 v[102:103], 0
	v_mov_b64_e32 v[104:105], 0
	v_mov_b64_e32 v[106:107], 0
	v_mov_b64_e32 v[108:109], 0
	v_mov_b64_e32 v[110:111], 0
	v_mov_b64_e32 v[112:113], 0
	v_mov_b64_e32 v[114:115], 0
	v_mov_b64_e32 v[116:117], 0
	v_mov_b64_e32 v[118:119], 0
	v_mov_b64_e32 v[120:121], 0
	v_mov_b64_e32 v[122:123], 0
	v_mov_b64_e32 v[124:125], 0
	v_mov_b64_e32 v[126:127], 0

.LBB0_250:
	s_ashr_i32 s23, s22, 31
	s_lshl_b64 s[24:25], s[22:23], 19
	s_add_u32 s24, s96, s24
	s_addc_u32 s25, s97, s25
	s_and_b64 s[26:27], s[4:5], exec
	s_cselect_b32 s7, s25, s13
	s_cselect_b32 s11, s24, s12
	s_ashr_i32 s21, s20, 31
	s_lshl_b64 s[26:27], s[20:21], 19
	s_add_u32 s26, s2, s26
	s_addc_u32 s27, s30, s27
	s_and_b64 s[28:29], s[4:5], exec
	s_cselect_b32 s21, s27, s15
	s_cselect_b32 s23, s26, s14
	s_add_u32 s12, s12, 0x40080
	s_addc_u32 s13, s13, 0
	s_add_u32 s38, s14, 0x100
	v_mov_b32_e32 v0, 0
	s_addc_u32 s39, s15, 0
	s_mov_b32 s54, -2
	v_mov_b32_e32 v1, 0
	v_mov_b64_e32 v[2:3], 0
	v_mov_b64_e32 v[4:5], 0
	v_mov_b64_e32 v[6:7], 0
	v_mov_b64_e32 v[8:9], 0
	v_mov_b64_e32 v[10:11], 0
	v_mov_b64_e32 v[12:13], 0
	v_mov_b64_e32 v[14:15], 0
	v_mov_b64_e32 v[16:17], 0
	v_mov_b64_e32 v[18:19], 0
	v_mov_b64_e32 v[20:21], 0
	v_mov_b64_e32 v[22:23], 0
	v_mov_b64_e32 v[24:25], 0
	v_mov_b64_e32 v[26:27], 0
	v_mov_b64_e32 v[28:29], 0
	v_mov_b64_e32 v[30:31], 0
	v_mov_b64_e32 v[32:33], 0
	v_mov_b64_e32 v[34:35], 0
	v_mov_b64_e32 v[36:37], 0
	v_mov_b64_e32 v[38:39], 0
	v_mov_b64_e32 v[40:41], 0
	v_mov_b64_e32 v[42:43], 0
	v_mov_b64_e32 v[44:45], 0
	v_mov_b64_e32 v[46:47], 0
	v_mov_b64_e32 v[48:49], 0
	v_mov_b64_e32 v[50:51], 0
	v_mov_b64_e32 v[52:53], 0
	v_mov_b64_e32 v[54:55], 0
	v_mov_b64_e32 v[56:57], 0
	v_mov_b64_e32 v[58:59], 0
	v_mov_b64_e32 v[60:61], 0
	v_mov_b64_e32 v[62:63], 0
	v_mov_b64_e32 v[64:65], 0
	v_mov_b64_e32 v[66:67], 0
	v_mov_b64_e32 v[68:69], 0
	v_mov_b64_e32 v[70:71], 0
	v_mov_b64_e32 v[72:73], 0
	v_mov_b64_e32 v[74:75], 0
	v_mov_b64_e32 v[76:77], 0
	v_mov_b64_e32 v[78:79], 0
	v_mov_b64_e32 v[80:81], 0
	v_mov_b64_e32 v[82:83], 0
	v_mov_b64_e32 v[84:85], 0
	v_mov_b64_e32 v[86:87], 0
	v_mov_b64_e32 v[88:89], 0
	v_mov_b64_e32 v[90:91], 0
	v_mov_b64_e32 v[92:93], 0
	v_mov_b64_e32 v[94:95], 0
	v_mov_b64_e32 v[96:97], 0
	v_mov_b64_e32 v[98:99], 0
	v_mov_b64_e32 v[100:101], 0
	v_mov_b64_e32 v[102:103], 0
	v_mov_b64_e32 v[104:105], 0
	v_mov_b64_e32 v[106:107], 0
	v_mov_b64_e32 v[108:109], 0
	v_mov_b64_e32 v[110:111], 0
	v_mov_b64_e32 v[112:113], 0
	v_mov_b64_e32 v[114:115], 0
	v_mov_b64_e32 v[116:117], 0
	v_mov_b64_e32 v[118:119], 0
	v_mov_b64_e32 v[120:121], 0
	v_mov_b64_e32 v[122:123], 0
	v_mov_b64_e32 v[124:125], 0
	v_mov_b64_e32 v[126:127], 0

.LBB0_585:
	s_ashr_i32 s23, s22, 31
	s_lshl_b64 s[14:15], s[22:23], 19
	s_add_u32 s24, s96, s14
	s_addc_u32 s25, s97, s15
	s_and_b64 s[14:15], s[4:5], exec
	s_cselect_b32 s7, s25, s11
	s_cselect_b32 s9, s24, s10
	s_ashr_i32 s21, s20, 31
	s_lshl_b64 s[14:15], s[20:21], 19
	s_add_u32 s26, s2, s14
	s_addc_u32 s27, s28, s15
	s_and_b64 s[14:15], s[4:5], exec
	s_cselect_b32 s21, s27, s13
	s_cselect_b32 s23, s26, s12
	s_add_u32 s10, s10, 0x40080
	s_addc_u32 s11, s11, 0
	s_add_u32 s38, s12, 0x100
	v_mov_b32_e32 v0, 0
	s_addc_u32 s39, s13, 0
	s_mov_b32 s54, -2
	v_mov_b32_e32 v1, 0
	v_mov_b64_e32 v[2:3], 0
	v_mov_b64_e32 v[4:5], 0
	v_mov_b64_e32 v[6:7], 0
	v_mov_b64_e32 v[8:9], 0
	v_mov_b64_e32 v[10:11], 0
	v_mov_b64_e32 v[12:13], 0
	v_mov_b64_e32 v[14:15], 0
	v_mov_b64_e32 v[16:17], 0
	v_mov_b64_e32 v[18:19], 0
	v_mov_b64_e32 v[20:21], 0
	v_mov_b64_e32 v[22:23], 0
	v_mov_b64_e32 v[24:25], 0
	v_mov_b64_e32 v[26:27], 0
	v_mov_b64_e32 v[28:29], 0
	v_mov_b64_e32 v[30:31], 0
	v_mov_b64_e32 v[32:33], 0
	v_mov_b64_e32 v[34:35], 0
	v_mov_b64_e32 v[36:37], 0
	v_mov_b64_e32 v[38:39], 0
	v_mov_b64_e32 v[40:41], 0
	v_mov_b64_e32 v[42:43], 0
	v_mov_b64_e32 v[44:45], 0
	v_mov_b64_e32 v[46:47], 0
	v_mov_b64_e32 v[48:49], 0
	v_mov_b64_e32 v[50:51], 0
	v_mov_b64_e32 v[52:53], 0
	v_mov_b64_e32 v[54:55], 0
	v_mov_b64_e32 v[56:57], 0
	v_mov_b64_e32 v[58:59], 0
	v_mov_b64_e32 v[60:61], 0
	v_mov_b64_e32 v[62:63], 0
	v_mov_b64_e32 v[64:65], 0
	v_mov_b64_e32 v[66:67], 0
	v_mov_b64_e32 v[68:69], 0
	v_mov_b64_e32 v[70:71], 0
	v_mov_b64_e32 v[72:73], 0
	v_mov_b64_e32 v[74:75], 0
	v_mov_b64_e32 v[76:77], 0
	v_mov_b64_e32 v[78:79], 0
	v_mov_b64_e32 v[80:81], 0
	v_mov_b64_e32 v[82:83], 0
	v_mov_b64_e32 v[84:85], 0
	v_mov_b64_e32 v[86:87], 0
	v_mov_b64_e32 v[88:89], 0
	v_mov_b64_e32 v[90:91], 0
	v_mov_b64_e32 v[92:93], 0
	v_mov_b64_e32 v[94:95], 0
	v_mov_b64_e32 v[96:97], 0
	v_mov_b64_e32 v[98:99], 0
	v_mov_b64_e32 v[100:101], 0
	v_mov_b64_e32 v[102:103], 0
	v_mov_b64_e32 v[104:105], 0
	v_mov_b64_e32 v[106:107], 0
	v_mov_b64_e32 v[108:109], 0
	v_mov_b64_e32 v[110:111], 0
	v_mov_b64_e32 v[112:113], 0
	v_mov_b64_e32 v[114:115], 0
	v_mov_b64_e32 v[116:117], 0
	v_mov_b64_e32 v[118:119], 0
	v_mov_b64_e32 v[120:121], 0
	v_mov_b64_e32 v[122:123], 0
	v_mov_b64_e32 v[124:125], 0
	v_mov_b64_e32 v[126:127], 0

.LBB0_855:
	s_ashr_i32 s23, s22, 31
	s_lshl_b64 s[4:5], s[22:23], 20
	s_add_u32 s24, s2, s4
	s_addc_u32 s25, s19, s5
	s_and_b64 s[4:5], s[6:7], exec
	s_cselect_b32 s4, s25, s11
	s_cselect_b32 s5, s24, s10
	s_ashr_i32 s21, s20, 31
	s_lshl_b64 s[26:27], s[20:21], 20
	s_add_u32 s26, s92, s26
	s_addc_u32 s27, s93, s27
	s_and_b64 s[30:31], s[6:7], exec
	s_cselect_b32 s21, s27, s29
	s_cselect_b32 s23, s26, s28
	s_add_u32 vcc_lo, s28, 0x100
	v_mov_b32_e32 v0, 0
	s_addc_u32 vcc_hi, s29, 0
	s_mov_b32 s56, -2
	v_mov_b32_e32 v1, 0
	v_mov_b64_e32 v[2:3], 0
	v_mov_b64_e32 v[4:5], 0
	v_mov_b64_e32 v[6:7], 0
	v_mov_b64_e32 v[8:9], 0
	v_mov_b64_e32 v[10:11], 0
	v_mov_b64_e32 v[12:13], 0
	v_mov_b64_e32 v[14:15], 0
	v_mov_b64_e32 v[16:17], 0
	v_mov_b64_e32 v[18:19], 0
	v_mov_b64_e32 v[20:21], 0
	v_mov_b64_e32 v[22:23], 0
	v_mov_b64_e32 v[24:25], 0
	v_mov_b64_e32 v[26:27], 0
	v_mov_b64_e32 v[28:29], 0
	v_mov_b64_e32 v[30:31], 0
	v_mov_b64_e32 v[32:33], 0
	v_mov_b64_e32 v[34:35], 0
	v_mov_b64_e32 v[36:37], 0
	v_mov_b64_e32 v[38:39], 0
	v_mov_b64_e32 v[40:41], 0
	v_mov_b64_e32 v[42:43], 0
	v_mov_b64_e32 v[44:45], 0
	v_mov_b64_e32 v[46:47], 0
	v_mov_b64_e32 v[48:49], 0
	v_mov_b64_e32 v[50:51], 0
	v_mov_b64_e32 v[52:53], 0
	v_mov_b64_e32 v[54:55], 0
	v_mov_b64_e32 v[56:57], 0
	v_mov_b64_e32 v[58:59], 0
	v_mov_b64_e32 v[60:61], 0
	v_mov_b64_e32 v[62:63], 0
	v_mov_b64_e32 v[64:65], 0
	v_mov_b64_e32 v[66:67], 0
	v_mov_b64_e32 v[68:69], 0
	v_mov_b64_e32 v[70:71], 0
	v_mov_b64_e32 v[72:73], 0
	v_mov_b64_e32 v[74:75], 0
	v_mov_b64_e32 v[76:77], 0
	v_mov_b64_e32 v[78:79], 0
	v_mov_b64_e32 v[80:81], 0
	v_mov_b64_e32 v[82:83], 0
	v_mov_b64_e32 v[84:85], 0
	v_mov_b64_e32 v[86:87], 0
	v_mov_b64_e32 v[88:89], 0
	v_mov_b64_e32 v[90:91], 0
	v_mov_b64_e32 v[92:93], 0
	v_mov_b64_e32 v[94:95], 0
	v_mov_b64_e32 v[96:97], 0
	v_mov_b64_e32 v[98:99], 0
	v_mov_b64_e32 v[100:101], 0
	v_mov_b64_e32 v[102:103], 0
	v_mov_b64_e32 v[104:105], 0
	v_mov_b64_e32 v[106:107], 0
	v_mov_b64_e32 v[108:109], 0
	v_mov_b64_e32 v[110:111], 0
	v_mov_b64_e32 v[112:113], 0
	v_mov_b64_e32 v[114:115], 0
	v_mov_b64_e32 v[116:117], 0
	v_mov_b64_e32 v[118:119], 0
	v_mov_b64_e32 v[120:121], 0
	v_mov_b64_e32 v[122:123], 0
	v_mov_b64_e32 v[124:125], 0
	v_mov_b64_e32 v[126:127], 0

.LBB0_1095:
	s_ashr_i32 s27, s26, 31
	s_lshl_b64 s[4:5], s[26:27], 19
	s_add_u32 s42, s96, s4
	s_addc_u32 s43, s97, s5
	s_and_b64 s[4:5], s[10:11], exec
	s_cselect_b32 s4, s43, s25
	s_cselect_b32 s5, s42, s24
	s_ashr_i32 s15, s14, 31
	s_lshl_b64 s[44:45], s[14:15], 19
	v_readlane_b32 s16, v254, 26
	v_readlane_b32 s17, v254, 27
	s_add_u32 s44, s16, s44
	s_addc_u32 s45, s17, s45
	s_and_b64 s[50:51], s[10:11], exec
	s_cselect_b32 s15, s45, s49
	s_cselect_b32 s27, s44, s48
	s_add_u32 s24, s24, 0x40080
	s_addc_u32 s25, s25, 0
	s_add_u32 s39, s48, 0x100
	v_mov_b32_e32 v0, 0
	s_addc_u32 s54, s49, 0
	s_mov_b32 s55, -2
	v_mov_b32_e32 v1, 0
	v_mov_b64_e32 v[2:3], 0
	v_mov_b64_e32 v[4:5], 0
	v_mov_b64_e32 v[6:7], 0
	v_mov_b64_e32 v[8:9], 0
	v_mov_b64_e32 v[10:11], 0
	v_mov_b64_e32 v[12:13], 0
	v_mov_b64_e32 v[14:15], 0
	v_mov_b64_e32 v[16:17], 0
	v_mov_b64_e32 v[18:19], 0
	v_mov_b64_e32 v[20:21], 0
	v_mov_b64_e32 v[22:23], 0
	v_mov_b64_e32 v[24:25], 0
	v_mov_b64_e32 v[26:27], 0
	v_mov_b64_e32 v[28:29], 0
	v_mov_b64_e32 v[30:31], 0
	v_mov_b64_e32 v[32:33], 0
	v_mov_b64_e32 v[34:35], 0
	v_mov_b64_e32 v[36:37], 0
	v_mov_b64_e32 v[38:39], 0
	v_mov_b64_e32 v[40:41], 0
	v_mov_b64_e32 v[42:43], 0
	v_mov_b64_e32 v[44:45], 0
	v_mov_b64_e32 v[46:47], 0
	v_mov_b64_e32 v[48:49], 0
	v_mov_b64_e32 v[50:51], 0
	v_mov_b64_e32 v[52:53], 0
	v_mov_b64_e32 v[54:55], 0
	v_mov_b64_e32 v[56:57], 0
	v_mov_b64_e32 v[58:59], 0
	v_mov_b64_e32 v[60:61], 0
	v_mov_b64_e32 v[62:63], 0
	v_mov_b64_e32 v[64:65], 0
	v_mov_b64_e32 v[66:67], 0
	v_mov_b64_e32 v[68:69], 0
	v_mov_b64_e32 v[70:71], 0
	v_mov_b64_e32 v[72:73], 0
	v_mov_b64_e32 v[74:75], 0
	v_mov_b64_e32 v[76:77], 0
	v_mov_b64_e32 v[78:79], 0
	v_mov_b64_e32 v[80:81], 0
	v_mov_b64_e32 v[82:83], 0
	v_mov_b64_e32 v[84:85], 0
	v_mov_b64_e32 v[86:87], 0
	v_mov_b64_e32 v[88:89], 0
	v_mov_b64_e32 v[90:91], 0
	v_mov_b64_e32 v[92:93], 0
	v_mov_b64_e32 v[94:95], 0
	v_mov_b64_e32 v[96:97], 0
	v_mov_b64_e32 v[98:99], 0
	v_mov_b64_e32 v[100:101], 0
	v_mov_b64_e32 v[102:103], 0
	v_mov_b64_e32 v[104:105], 0
	v_mov_b64_e32 v[106:107], 0
	v_mov_b64_e32 v[108:109], 0
	v_mov_b64_e32 v[110:111], 0
	v_mov_b64_e32 v[112:113], 0
	v_mov_b64_e32 v[114:115], 0
	v_mov_b64_e32 v[116:117], 0
	v_mov_b64_e32 v[118:119], 0
	v_mov_b64_e32 v[120:121], 0
	v_mov_b64_e32 v[122:123], 0
	v_mov_b64_e32 v[124:125], 0
	v_mov_b64_e32 v[126:127], 0

.LBB0_1175:
	s_add_u32 s4, s46, 0x100
	v_mov_b32_e32 v0, 0
	s_addc_u32 s5, s47, 0
	s_mov_b32 s66, -2
	v_mov_b32_e32 v1, 0
	v_mov_b64_e32 v[2:3], 0
	v_mov_b64_e32 v[4:5], 0
	v_mov_b64_e32 v[6:7], 0
	v_mov_b64_e32 v[8:9], 0
	v_mov_b64_e32 v[10:11], 0
	v_mov_b64_e32 v[12:13], 0
	v_mov_b64_e32 v[14:15], 0
	v_mov_b64_e32 v[16:17], 0
	v_mov_b64_e32 v[18:19], 0
	v_mov_b64_e32 v[20:21], 0
	v_mov_b64_e32 v[22:23], 0
	v_mov_b64_e32 v[24:25], 0
	v_mov_b64_e32 v[26:27], 0
	v_mov_b64_e32 v[28:29], 0
	v_mov_b64_e32 v[30:31], 0
	v_mov_b64_e32 v[32:33], 0
	v_mov_b64_e32 v[34:35], 0
	v_mov_b64_e32 v[36:37], 0
	v_mov_b64_e32 v[38:39], 0
	v_mov_b64_e32 v[40:41], 0
	v_mov_b64_e32 v[42:43], 0
	v_mov_b64_e32 v[44:45], 0
	v_mov_b64_e32 v[46:47], 0
	v_mov_b64_e32 v[48:49], 0
	v_mov_b64_e32 v[50:51], 0
	v_mov_b64_e32 v[52:53], 0
	v_mov_b64_e32 v[54:55], 0
	v_mov_b64_e32 v[56:57], 0
	v_mov_b64_e32 v[58:59], 0
	v_mov_b64_e32 v[60:61], 0
	v_mov_b64_e32 v[62:63], 0
	v_mov_b64_e32 v[64:65], 0
	v_mov_b64_e32 v[66:67], 0
	v_mov_b64_e32 v[68:69], 0
	v_mov_b64_e32 v[70:71], 0
	v_mov_b64_e32 v[72:73], 0
	v_mov_b64_e32 v[74:75], 0
	v_mov_b64_e32 v[76:77], 0
	v_mov_b64_e32 v[78:79], 0
	v_mov_b64_e32 v[80:81], 0
	v_mov_b64_e32 v[82:83], 0
	v_mov_b64_e32 v[84:85], 0
	v_mov_b64_e32 v[86:87], 0
	v_mov_b64_e32 v[88:89], 0
	v_mov_b64_e32 v[90:91], 0
	v_mov_b64_e32 v[92:93], 0
	v_mov_b64_e32 v[94:95], 0
	v_mov_b64_e32 v[96:97], 0
	v_mov_b64_e32 v[98:99], 0
	v_mov_b64_e32 v[100:101], 0
	v_mov_b64_e32 v[102:103], 0
	v_mov_b64_e32 v[104:105], 0
	v_mov_b64_e32 v[106:107], 0
	v_mov_b64_e32 v[108:109], 0
	v_mov_b64_e32 v[110:111], 0
	v_mov_b64_e32 v[112:113], 0
	v_mov_b64_e32 v[114:115], 0
	v_mov_b64_e32 v[116:117], 0
	v_mov_b64_e32 v[118:119], 0
	v_mov_b64_e32 v[120:121], 0
	v_mov_b64_e32 v[122:123], 0
	v_mov_b64_e32 v[124:125], 0
	v_mov_b64_e32 v[126:127], 0

.LBB0_1333:
	s_ashr_i32 s49, s48, 31
	s_lshl_b64 s[4:5], s[48:49], 19
	s_add_u32 s50, s96, s4
	s_addc_u32 s51, s97, s5
	s_and_b64 s[4:5], s[8:9], exec
	s_cselect_b32 s4, s51, s15
	s_cselect_b32 s5, s50, s14
	s_ashr_i32 s47, s46, 31
	s_lshl_b64 s[54:55], s[46:47], 19
	s_add_u32 s54, s80, s54
	s_addc_u32 s55, s81, s55
	s_and_b64 s[64:65], s[8:9], exec
	s_cselect_b32 s11, s55, s25
	s_cselect_b32 s13, s54, s24
	s_add_u32 s14, s14, 0x40080
	s_addc_u32 s15, s15, 0
	s_add_u32 s47, s24, 0x100
	v_mov_b32_e32 v0, 0
	s_addc_u32 s49, s25, 0
	s_mov_b32 s66, -2
	v_mov_b32_e32 v1, 0
	v_mov_b64_e32 v[2:3], 0
	v_mov_b64_e32 v[4:5], 0
	v_mov_b64_e32 v[6:7], 0
	v_mov_b64_e32 v[8:9], 0
	v_mov_b64_e32 v[10:11], 0
	v_mov_b64_e32 v[12:13], 0
	v_mov_b64_e32 v[14:15], 0
	v_mov_b64_e32 v[16:17], 0
	v_mov_b64_e32 v[18:19], 0
	v_mov_b64_e32 v[20:21], 0
	v_mov_b64_e32 v[22:23], 0
	v_mov_b64_e32 v[24:25], 0
	v_mov_b64_e32 v[26:27], 0
	v_mov_b64_e32 v[28:29], 0
	v_mov_b64_e32 v[30:31], 0
	v_mov_b64_e32 v[32:33], 0
	v_mov_b64_e32 v[34:35], 0
	v_mov_b64_e32 v[36:37], 0
	v_mov_b64_e32 v[38:39], 0
	v_mov_b64_e32 v[40:41], 0
	v_mov_b64_e32 v[42:43], 0
	v_mov_b64_e32 v[44:45], 0
	v_mov_b64_e32 v[46:47], 0
	v_mov_b64_e32 v[48:49], 0
	v_mov_b64_e32 v[50:51], 0
	v_mov_b64_e32 v[52:53], 0
	v_mov_b64_e32 v[54:55], 0
	v_mov_b64_e32 v[56:57], 0
	v_mov_b64_e32 v[58:59], 0
	v_mov_b64_e32 v[60:61], 0
	v_mov_b64_e32 v[62:63], 0
	v_mov_b64_e32 v[64:65], 0
	v_mov_b64_e32 v[66:67], 0
	v_mov_b64_e32 v[68:69], 0
	v_mov_b64_e32 v[70:71], 0
	v_mov_b64_e32 v[72:73], 0
	v_mov_b64_e32 v[74:75], 0
	v_mov_b64_e32 v[76:77], 0
	v_mov_b64_e32 v[78:79], 0
	v_mov_b64_e32 v[80:81], 0
	v_mov_b64_e32 v[82:83], 0
	v_mov_b64_e32 v[84:85], 0
	v_mov_b64_e32 v[86:87], 0
	v_mov_b64_e32 v[88:89], 0
	v_mov_b64_e32 v[90:91], 0
	v_mov_b64_e32 v[92:93], 0
	v_mov_b64_e32 v[94:95], 0
	v_mov_b64_e32 v[96:97], 0
	v_mov_b64_e32 v[98:99], 0
	v_mov_b64_e32 v[100:101], 0
	v_mov_b64_e32 v[102:103], 0
	v_mov_b64_e32 v[104:105], 0
	v_mov_b64_e32 v[106:107], 0
	v_mov_b64_e32 v[108:109], 0
	v_mov_b64_e32 v[110:111], 0
	v_mov_b64_e32 v[112:113], 0
	v_mov_b64_e32 v[114:115], 0
	v_mov_b64_e32 v[116:117], 0
	v_mov_b64_e32 v[118:119], 0
	v_mov_b64_e32 v[120:121], 0
	v_mov_b64_e32 v[122:123], 0
	v_mov_b64_e32 v[124:125], 0
	v_mov_b64_e32 v[126:127], 0

.LBB0_1496:
	s_ashr_i32 s43, s42, 31
	s_lshl_b64 s[4:5], s[42:43], 19
	s_add_u32 s44, s96, s4
	s_addc_u32 s45, s97, s5
	s_and_b64 s[4:5], s[8:9], exec
	s_cselect_b32 s4, s45, s25
	s_cselect_b32 s5, s44, s24
	s_ashr_i32 s39, s38, 31
	s_lshl_b64 s[46:47], s[38:39], 19
	s_add_u32 s46, s2, s46
	s_addc_u32 s47, s6, s47
	s_and_b64 s[54:55], s[8:9], exec
	s_cselect_b32 s39, s47, s51
	s_cselect_b32 s43, s46, s50
	s_add_u32 s86, s50, 0x100
	v_mov_b32_e32 v0, 0
	s_addc_u32 s87, s51, 0
	s_mov_b32 s68, -2
	v_mov_b32_e32 v1, 0
	v_mov_b64_e32 v[2:3], 0
	v_mov_b64_e32 v[4:5], 0
	v_mov_b64_e32 v[6:7], 0
	v_mov_b64_e32 v[8:9], 0
	v_mov_b64_e32 v[10:11], 0
	v_mov_b64_e32 v[12:13], 0
	v_mov_b64_e32 v[14:15], 0
	v_mov_b64_e32 v[16:17], 0
	v_mov_b64_e32 v[18:19], 0
	v_mov_b64_e32 v[20:21], 0
	v_mov_b64_e32 v[22:23], 0
	v_mov_b64_e32 v[24:25], 0
	v_mov_b64_e32 v[26:27], 0
	v_mov_b64_e32 v[28:29], 0
	v_mov_b64_e32 v[30:31], 0
	v_mov_b64_e32 v[32:33], 0
	v_mov_b64_e32 v[34:35], 0
	v_mov_b64_e32 v[36:37], 0
	v_mov_b64_e32 v[38:39], 0
	v_mov_b64_e32 v[40:41], 0
	v_mov_b64_e32 v[42:43], 0
	v_mov_b64_e32 v[44:45], 0
	v_mov_b64_e32 v[46:47], 0
	v_mov_b64_e32 v[48:49], 0
	v_mov_b64_e32 v[50:51], 0
	v_mov_b64_e32 v[52:53], 0
	v_mov_b64_e32 v[54:55], 0
	v_mov_b64_e32 v[56:57], 0
	v_mov_b64_e32 v[58:59], 0
	v_mov_b64_e32 v[60:61], 0
	v_mov_b64_e32 v[62:63], 0
	v_mov_b64_e32 v[64:65], 0
	v_mov_b64_e32 v[66:67], 0
	v_mov_b64_e32 v[68:69], 0
	v_mov_b64_e32 v[70:71], 0
	v_mov_b64_e32 v[72:73], 0
	v_mov_b64_e32 v[74:75], 0
	v_mov_b64_e32 v[76:77], 0
	v_mov_b64_e32 v[78:79], 0
	v_mov_b64_e32 v[80:81], 0
	v_mov_b64_e32 v[82:83], 0
	v_mov_b64_e32 v[84:85], 0
	v_mov_b64_e32 v[86:87], 0
	v_mov_b64_e32 v[88:89], 0
	v_mov_b64_e32 v[90:91], 0
	v_mov_b64_e32 v[92:93], 0
	v_mov_b64_e32 v[94:95], 0
	v_mov_b64_e32 v[96:97], 0
	v_mov_b64_e32 v[98:99], 0
	v_mov_b64_e32 v[100:101], 0
	v_mov_b64_e32 v[102:103], 0
	v_mov_b64_e32 v[104:105], 0
	v_mov_b64_e32 v[106:107], 0
	v_mov_b64_e32 v[108:109], 0
	v_mov_b64_e32 v[110:111], 0
	v_mov_b64_e32 v[112:113], 0
	v_mov_b64_e32 v[114:115], 0
	v_mov_b64_e32 v[116:117], 0
	v_mov_b64_e32 v[118:119], 0
	v_mov_b64_e32 v[120:121], 0
	v_mov_b64_e32 v[122:123], 0
	v_mov_b64_e32 v[124:125], 0
	v_mov_b64_e32 v[126:127], 0

.LBB0_1765:
	s_ashr_i32 s49, s48, 31
	s_lshl_b64 s[4:5], s[48:49], 19
	s_add_u32 s50, s96, s4
	s_addc_u32 s51, s97, s5
	s_and_b64 s[4:5], s[8:9], exec
	s_cselect_b32 s4, s51, s25
	s_cselect_b32 s5, s50, s24
	s_ashr_i32 s47, s46, 31
	s_lshl_b64 s[54:55], s[46:47], 19
	s_add_u32 s54, s58, s54
	s_addc_u32 s55, s59, s55
	s_and_b64 s[68:69], s[8:9], exec
	s_cselect_b32 s47, s55, s75
	s_cselect_b32 s49, s54, s74
	s_add_u32 s86, s74, 0x100
	v_mov_b32_e32 v0, 0
	s_addc_u32 s87, s75, 0
	s_mov_b32 s68, -2
	v_mov_b32_e32 v1, 0
	v_mov_b64_e32 v[2:3], 0
	v_mov_b64_e32 v[4:5], 0
	v_mov_b64_e32 v[6:7], 0
	v_mov_b64_e32 v[8:9], 0
	v_mov_b64_e32 v[10:11], 0
	v_mov_b64_e32 v[12:13], 0
	v_mov_b64_e32 v[14:15], 0
	v_mov_b64_e32 v[16:17], 0
	v_mov_b64_e32 v[18:19], 0
	v_mov_b64_e32 v[20:21], 0
	v_mov_b64_e32 v[22:23], 0
	v_mov_b64_e32 v[24:25], 0
	v_mov_b64_e32 v[26:27], 0
	v_mov_b64_e32 v[28:29], 0
	v_mov_b64_e32 v[30:31], 0
	v_mov_b64_e32 v[32:33], 0
	v_mov_b64_e32 v[34:35], 0
	v_mov_b64_e32 v[36:37], 0
	v_mov_b64_e32 v[38:39], 0
	v_mov_b64_e32 v[40:41], 0
	v_mov_b64_e32 v[42:43], 0
	v_mov_b64_e32 v[44:45], 0
	v_mov_b64_e32 v[46:47], 0
	v_mov_b64_e32 v[48:49], 0
	v_mov_b64_e32 v[50:51], 0
	v_mov_b64_e32 v[52:53], 0
	v_mov_b64_e32 v[54:55], 0
	v_mov_b64_e32 v[56:57], 0
	v_mov_b64_e32 v[58:59], 0
	v_mov_b64_e32 v[60:61], 0
	v_mov_b64_e32 v[62:63], 0
	v_mov_b64_e32 v[64:65], 0
	v_mov_b64_e32 v[66:67], 0
	v_mov_b64_e32 v[68:69], 0
	v_mov_b64_e32 v[70:71], 0
	v_mov_b64_e32 v[72:73], 0
	v_mov_b64_e32 v[74:75], 0
	v_mov_b64_e32 v[76:77], 0
	v_mov_b64_e32 v[78:79], 0
	v_mov_b64_e32 v[80:81], 0
	v_mov_b64_e32 v[82:83], 0
	v_mov_b64_e32 v[84:85], 0
	v_mov_b64_e32 v[86:87], 0
	v_mov_b64_e32 v[88:89], 0
	v_mov_b64_e32 v[90:91], 0
	v_mov_b64_e32 v[92:93], 0
	v_mov_b64_e32 v[94:95], 0
	v_mov_b64_e32 v[96:97], 0
	v_mov_b64_e32 v[98:99], 0
	v_mov_b64_e32 v[100:101], 0
	v_mov_b64_e32 v[102:103], 0
	v_mov_b64_e32 v[104:105], 0
	v_mov_b64_e32 v[106:107], 0
	v_mov_b64_e32 v[108:109], 0
	v_mov_b64_e32 v[110:111], 0
	v_mov_b64_e32 v[112:113], 0
	v_mov_b64_e32 v[114:115], 0
	v_mov_b64_e32 v[116:117], 0
	v_mov_b64_e32 v[118:119], 0
	v_mov_b64_e32 v[120:121], 0
	v_mov_b64_e32 v[122:123], 0
	v_mov_b64_e32 v[124:125], 0
	v_mov_b64_e32 v[126:127], 0

.LBB0_1913:
	s_ashr_i32 s41, s40, 31
	s_lshl_b64 s[4:5], s[40:41], 19
	s_add_u32 s42, s96, s4
	s_addc_u32 s43, s97, s5
	s_and_b64 s[4:5], s[10:11], exec
	s_cselect_b32 s4, s43, s25
	s_cselect_b32 s5, s42, s24
	s_ashr_i32 s39, s38, 31
	s_lshl_b64 s[44:45], s[38:39], 19
	v_readlane_b32 s16, v255, 27
	v_readlane_b32 s17, v255, 28
	s_add_u32 s44, s16, s44
	s_addc_u32 s45, s17, s45
	s_and_b64 s[50:51], s[10:11], exec
	s_cselect_b32 s39, s45, s49
	s_cselect_b32 s41, s44, s48
	s_add_u32 s24, s24, 0x40080
	s_addc_u32 s25, s25, 0
	s_add_u32 s67, s48, 0x100
	v_mov_b32_e32 v0, 0
	s_addc_u32 s74, s49, 0
	s_mov_b32 s75, -2
	v_mov_b32_e32 v1, 0
	v_mov_b64_e32 v[2:3], 0
	v_mov_b64_e32 v[4:5], 0
	v_mov_b64_e32 v[6:7], 0
	v_mov_b64_e32 v[8:9], 0
	v_mov_b64_e32 v[10:11], 0
	v_mov_b64_e32 v[12:13], 0
	v_mov_b64_e32 v[14:15], 0
	v_mov_b64_e32 v[16:17], 0
	v_mov_b64_e32 v[18:19], 0
	v_mov_b64_e32 v[20:21], 0
	v_mov_b64_e32 v[22:23], 0
	v_mov_b64_e32 v[24:25], 0
	v_mov_b64_e32 v[26:27], 0
	v_mov_b64_e32 v[28:29], 0
	v_mov_b64_e32 v[30:31], 0
	v_mov_b64_e32 v[32:33], 0
	v_mov_b64_e32 v[34:35], 0
	v_mov_b64_e32 v[36:37], 0
	v_mov_b64_e32 v[38:39], 0
	v_mov_b64_e32 v[40:41], 0
	v_mov_b64_e32 v[42:43], 0
	v_mov_b64_e32 v[44:45], 0
	v_mov_b64_e32 v[46:47], 0
	v_mov_b64_e32 v[48:49], 0
	v_mov_b64_e32 v[50:51], 0
	v_mov_b64_e32 v[52:53], 0
	v_mov_b64_e32 v[54:55], 0
	v_mov_b64_e32 v[56:57], 0
	v_mov_b64_e32 v[58:59], 0
	v_mov_b64_e32 v[60:61], 0
	v_mov_b64_e32 v[62:63], 0
	v_mov_b64_e32 v[64:65], 0
	v_mov_b64_e32 v[66:67], 0
	v_mov_b64_e32 v[68:69], 0
	v_mov_b64_e32 v[70:71], 0
	v_mov_b64_e32 v[72:73], 0
	v_mov_b64_e32 v[74:75], 0
	v_mov_b64_e32 v[76:77], 0
	v_mov_b64_e32 v[78:79], 0
	v_mov_b64_e32 v[80:81], 0
	v_mov_b64_e32 v[82:83], 0
	v_mov_b64_e32 v[84:85], 0
	v_mov_b64_e32 v[86:87], 0
	v_mov_b64_e32 v[88:89], 0
	v_mov_b64_e32 v[90:91], 0
	v_mov_b64_e32 v[92:93], 0
	v_mov_b64_e32 v[94:95], 0
	v_mov_b64_e32 v[96:97], 0
	v_mov_b64_e32 v[98:99], 0
	v_mov_b64_e32 v[100:101], 0
	v_mov_b64_e32 v[102:103], 0
	v_mov_b64_e32 v[104:105], 0
	v_mov_b64_e32 v[106:107], 0
	v_mov_b64_e32 v[108:109], 0
	v_mov_b64_e32 v[110:111], 0
	v_mov_b64_e32 v[112:113], 0
	v_mov_b64_e32 v[114:115], 0
	v_mov_b64_e32 v[116:117], 0
	v_mov_b64_e32 v[118:119], 0
	v_mov_b64_e32 v[120:121], 0
	v_mov_b64_e32 v[122:123], 0
	v_mov_b64_e32 v[124:125], 0
	v_mov_b64_e32 v[126:127], 0

.LBB0_1993:
	s_add_u32 s4, s48, 0x100
	v_mov_b32_e32 v0, 0
	s_addc_u32 s5, s49, 0
	s_mov_b32 s68, -2
	v_mov_b32_e32 v1, 0
	v_mov_b64_e32 v[2:3], 0
	v_mov_b64_e32 v[4:5], 0
	v_mov_b64_e32 v[6:7], 0
	v_mov_b64_e32 v[8:9], 0
	v_mov_b64_e32 v[10:11], 0
	v_mov_b64_e32 v[12:13], 0
	v_mov_b64_e32 v[14:15], 0
	v_mov_b64_e32 v[16:17], 0
	v_mov_b64_e32 v[18:19], 0
	v_mov_b64_e32 v[20:21], 0
	v_mov_b64_e32 v[22:23], 0
	v_mov_b64_e32 v[24:25], 0
	v_mov_b64_e32 v[26:27], 0
	v_mov_b64_e32 v[28:29], 0
	v_mov_b64_e32 v[30:31], 0
	v_mov_b64_e32 v[32:33], 0
	v_mov_b64_e32 v[34:35], 0
	v_mov_b64_e32 v[36:37], 0
	v_mov_b64_e32 v[38:39], 0
	v_mov_b64_e32 v[40:41], 0
	v_mov_b64_e32 v[42:43], 0
	v_mov_b64_e32 v[44:45], 0
	v_mov_b64_e32 v[46:47], 0
	v_mov_b64_e32 v[48:49], 0
	v_mov_b64_e32 v[50:51], 0
	v_mov_b64_e32 v[52:53], 0
	v_mov_b64_e32 v[54:55], 0
	v_mov_b64_e32 v[56:57], 0
	v_mov_b64_e32 v[58:59], 0
	v_mov_b64_e32 v[60:61], 0
	v_mov_b64_e32 v[62:63], 0
	v_mov_b64_e32 v[64:65], 0
	v_mov_b64_e32 v[66:67], 0
	v_mov_b64_e32 v[68:69], 0
	v_mov_b64_e32 v[70:71], 0
	v_mov_b64_e32 v[72:73], 0
	v_mov_b64_e32 v[74:75], 0
	v_mov_b64_e32 v[76:77], 0
	v_mov_b64_e32 v[78:79], 0
	v_mov_b64_e32 v[80:81], 0
	v_mov_b64_e32 v[82:83], 0
	v_mov_b64_e32 v[84:85], 0
	v_mov_b64_e32 v[86:87], 0
	v_mov_b64_e32 v[88:89], 0
	v_mov_b64_e32 v[90:91], 0
	v_mov_b64_e32 v[92:93], 0
	v_mov_b64_e32 v[94:95], 0
	v_mov_b64_e32 v[96:97], 0
	v_mov_b64_e32 v[98:99], 0
	v_mov_b64_e32 v[100:101], 0
	v_mov_b64_e32 v[102:103], 0
	v_mov_b64_e32 v[104:105], 0
	v_mov_b64_e32 v[106:107], 0
	v_mov_b64_e32 v[108:109], 0
	v_mov_b64_e32 v[110:111], 0
	v_mov_b64_e32 v[112:113], 0
	v_mov_b64_e32 v[114:115], 0
	v_mov_b64_e32 v[116:117], 0
	v_mov_b64_e32 v[118:119], 0
	v_mov_b64_e32 v[120:121], 0
	v_mov_b64_e32 v[122:123], 0
	v_mov_b64_e32 v[124:125], 0
	v_mov_b64_e32 v[126:127], 0

.LBB0_2151:
	s_ashr_i32 s49, s48, 31
	s_lshl_b64 s[4:5], s[48:49], 19
	s_add_u32 s50, s96, s4
	s_addc_u32 s51, s97, s5
	s_and_b64 s[4:5], s[10:11], exec
	s_cselect_b32 s4, s51, s17
	s_cselect_b32 s5, s50, s16
	s_ashr_i32 s47, s46, 31
	s_lshl_b64 s[24:25], s[46:47], 19
	s_add_u32 s54, s78, s24
	s_addc_u32 s55, s79, s25
	s_and_b64 s[24:25], s[10:11], exec
	s_cselect_b32 s13, s55, s19
	s_cselect_b32 s15, s54, s18
	s_add_u32 s16, s16, 0x40080
	s_addc_u32 s17, s17, 0
	s_add_u32 s47, s18, 0x100
	v_mov_b32_e32 v0, 0
	s_addc_u32 s49, s19, 0
	s_mov_b32 s66, -2
	v_mov_b32_e32 v1, 0
	v_mov_b64_e32 v[2:3], 0
	v_mov_b64_e32 v[4:5], 0
	v_mov_b64_e32 v[6:7], 0
	v_mov_b64_e32 v[8:9], 0
	v_mov_b64_e32 v[10:11], 0
	v_mov_b64_e32 v[12:13], 0
	v_mov_b64_e32 v[14:15], 0
	v_mov_b64_e32 v[16:17], 0
	v_mov_b64_e32 v[18:19], 0
	v_mov_b64_e32 v[20:21], 0
	v_mov_b64_e32 v[22:23], 0
	v_mov_b64_e32 v[24:25], 0
	v_mov_b64_e32 v[26:27], 0
	v_mov_b64_e32 v[28:29], 0
	v_mov_b64_e32 v[30:31], 0
	v_mov_b64_e32 v[32:33], 0
	v_mov_b64_e32 v[34:35], 0
	v_mov_b64_e32 v[36:37], 0
	v_mov_b64_e32 v[38:39], 0
	v_mov_b64_e32 v[40:41], 0
	v_mov_b64_e32 v[42:43], 0
	v_mov_b64_e32 v[44:45], 0
	v_mov_b64_e32 v[46:47], 0
	v_mov_b64_e32 v[48:49], 0
	v_mov_b64_e32 v[50:51], 0
	v_mov_b64_e32 v[52:53], 0
	v_mov_b64_e32 v[54:55], 0
	v_mov_b64_e32 v[56:57], 0
	v_mov_b64_e32 v[58:59], 0
	v_mov_b64_e32 v[60:61], 0
	v_mov_b64_e32 v[62:63], 0
	v_mov_b64_e32 v[64:65], 0
	v_mov_b64_e32 v[66:67], 0
	v_mov_b64_e32 v[68:69], 0
	v_mov_b64_e32 v[70:71], 0
	v_mov_b64_e32 v[72:73], 0
	v_mov_b64_e32 v[74:75], 0
	v_mov_b64_e32 v[76:77], 0
	v_mov_b64_e32 v[78:79], 0
	v_mov_b64_e32 v[80:81], 0
	v_mov_b64_e32 v[82:83], 0
	v_mov_b64_e32 v[84:85], 0
	v_mov_b64_e32 v[86:87], 0
	v_mov_b64_e32 v[88:89], 0
	v_mov_b64_e32 v[90:91], 0
	v_mov_b64_e32 v[92:93], 0
	v_mov_b64_e32 v[94:95], 0
	v_mov_b64_e32 v[96:97], 0
	v_mov_b64_e32 v[98:99], 0
	v_mov_b64_e32 v[100:101], 0
	v_mov_b64_e32 v[102:103], 0
	v_mov_b64_e32 v[104:105], 0
	v_mov_b64_e32 v[106:107], 0
	v_mov_b64_e32 v[108:109], 0
	v_mov_b64_e32 v[110:111], 0
	v_mov_b64_e32 v[112:113], 0
	v_mov_b64_e32 v[114:115], 0
	v_mov_b64_e32 v[116:117], 0
	v_mov_b64_e32 v[118:119], 0
	v_mov_b64_e32 v[120:121], 0
	v_mov_b64_e32 v[122:123], 0
	v_mov_b64_e32 v[124:125], 0
	v_mov_b64_e32 v[126:127], 0

.LBB0_2529:
	s_ashr_i32 s51, s50, 31
	s_lshl_b64 s[4:5], s[50:51], 18
	s_add_u32 s54, s56, s4
	s_addc_u32 s55, s57, s5
	s_and_b64 s[4:5], s[10:11], exec
	s_cselect_b32 s4, s55, s1
	s_cselect_b32 s5, s54, s0
	s_ashr_i32 s49, s48, 31
	s_lshl_b64 s[18:19], s[48:49], 18
	s_add_u32 s74, s92, s18
	s_addc_u32 s75, s93, s19
	s_and_b64 s[18:19], s[10:11], exec
	s_cselect_b32 s13, s75, s17
	s_cselect_b32 s15, s74, s16
	s_add_u32 s0, s0, 0x20080
	s_addc_u32 s1, s1, 0
	s_add_u32 s49, s16, 0x100
	v_mov_b32_e32 v0, 0
	s_addc_u32 s51, s17, 0
	s_mov_b32 s64, -2
	v_mov_b32_e32 v1, 0
	v_mov_b64_e32 v[2:3], 0
	v_mov_b64_e32 v[4:5], 0
	v_mov_b64_e32 v[6:7], 0
	v_mov_b64_e32 v[8:9], 0
	v_mov_b64_e32 v[10:11], 0
	v_mov_b64_e32 v[12:13], 0
	v_mov_b64_e32 v[14:15], 0
	v_mov_b64_e32 v[16:17], 0
	v_mov_b64_e32 v[18:19], 0
	v_mov_b64_e32 v[20:21], 0
	v_mov_b64_e32 v[22:23], 0
	v_mov_b64_e32 v[24:25], 0
	v_mov_b64_e32 v[26:27], 0
	v_mov_b64_e32 v[28:29], 0
	v_mov_b64_e32 v[30:31], 0
	v_mov_b64_e32 v[32:33], 0
	v_mov_b64_e32 v[34:35], 0
	v_mov_b64_e32 v[36:37], 0
	v_mov_b64_e32 v[38:39], 0
	v_mov_b64_e32 v[40:41], 0
	v_mov_b64_e32 v[42:43], 0
	v_mov_b64_e32 v[44:45], 0
	v_mov_b64_e32 v[46:47], 0
	v_mov_b64_e32 v[48:49], 0
	v_mov_b64_e32 v[50:51], 0
	v_mov_b64_e32 v[52:53], 0
	v_mov_b64_e32 v[54:55], 0
	v_mov_b64_e32 v[56:57], 0
	v_mov_b64_e32 v[58:59], 0
	v_mov_b64_e32 v[60:61], 0
	v_mov_b64_e32 v[62:63], 0
	v_mov_b64_e32 v[64:65], 0
	v_mov_b64_e32 v[66:67], 0
	v_mov_b64_e32 v[68:69], 0
	v_mov_b64_e32 v[70:71], 0
	v_mov_b64_e32 v[72:73], 0
	v_mov_b64_e32 v[74:75], 0
	v_mov_b64_e32 v[76:77], 0
	v_mov_b64_e32 v[78:79], 0
	v_mov_b64_e32 v[80:81], 0
	v_mov_b64_e32 v[82:83], 0
	v_mov_b64_e32 v[84:85], 0
	v_mov_b64_e32 v[86:87], 0
	v_mov_b64_e32 v[88:89], 0
	v_mov_b64_e32 v[90:91], 0
	v_mov_b64_e32 v[92:93], 0
	v_mov_b64_e32 v[94:95], 0
	v_mov_b64_e32 v[96:97], 0
	v_mov_b64_e32 v[98:99], 0
	v_mov_b64_e32 v[100:101], 0
	v_mov_b64_e32 v[102:103], 0
	v_mov_b64_e32 v[104:105], 0
	v_mov_b64_e32 v[106:107], 0
	v_mov_b64_e32 v[108:109], 0
	v_mov_b64_e32 v[110:111], 0
	v_mov_b64_e32 v[112:113], 0
	v_mov_b64_e32 v[114:115], 0
	v_mov_b64_e32 v[116:117], 0
	v_mov_b64_e32 v[118:119], 0
	v_mov_b64_e32 v[120:121], 0
	v_mov_b64_e32 v[122:123], 0
	v_mov_b64_e32 v[124:125], 0
	v_mov_b64_e32 v[126:127], 0

.LBB0_2627:
	s_ashr_i32 s23, s22, 31
	s_lshl_b64 s[4:5], s[22:23], 17
	s_add_u32 s24, s38, s4
	s_addc_u32 s25, s39, s5
	s_and_b64 s[4:5], s[10:11], exec
	s_cselect_b32 s4, s25, s49
	s_cselect_b32 s5, s24, s48
	s_ashr_i32 s21, s20, 31
	s_lshl_b64 s[42:43], s[20:21], 17
	s_add_u32 s42, s2, s42
	s_addc_u32 s43, s6, s43
	s_and_b64 s[50:51], s[10:11], exec
	v_mov_b32_e32 v0, 0
	s_cselect_b32 s21, s43, s47
	s_cselect_b32 s23, s42, s46
	s_mov_b32 s64, 0
	s_mov_b64 s[50:51], -1
	s_mov_b64 s[54:55], 0
	v_mov_b32_e32 v1, 0
	v_mov_b64_e32 v[2:3], 0
	v_mov_b64_e32 v[4:5], 0
	v_mov_b64_e32 v[6:7], 0
	v_mov_b64_e32 v[8:9], 0
	v_mov_b64_e32 v[10:11], 0
	v_mov_b64_e32 v[12:13], 0
	v_mov_b64_e32 v[14:15], 0
	v_mov_b64_e32 v[16:17], 0
	v_mov_b64_e32 v[18:19], 0
	v_mov_b64_e32 v[20:21], 0
	v_mov_b64_e32 v[22:23], 0
	v_mov_b64_e32 v[24:25], 0
	v_mov_b64_e32 v[26:27], 0
	v_mov_b64_e32 v[28:29], 0
	v_mov_b64_e32 v[30:31], 0
	v_mov_b64_e32 v[32:33], 0
	v_mov_b64_e32 v[34:35], 0
	v_mov_b64_e32 v[36:37], 0
	v_mov_b64_e32 v[38:39], 0
	v_mov_b64_e32 v[40:41], 0
	v_mov_b64_e32 v[42:43], 0
	v_mov_b64_e32 v[44:45], 0
	v_mov_b64_e32 v[46:47], 0
	v_mov_b64_e32 v[48:49], 0
	v_mov_b64_e32 v[50:51], 0
	v_mov_b64_e32 v[52:53], 0
	v_mov_b64_e32 v[54:55], 0
	v_mov_b64_e32 v[56:57], 0
	v_mov_b64_e32 v[58:59], 0
	v_mov_b64_e32 v[60:61], 0
	v_mov_b64_e32 v[62:63], 0
	v_mov_b64_e32 v[64:65], 0
	v_mov_b64_e32 v[66:67], 0
	v_mov_b64_e32 v[68:69], 0
	v_mov_b64_e32 v[70:71], 0
	v_mov_b64_e32 v[72:73], 0
	v_mov_b64_e32 v[74:75], 0
	v_mov_b64_e32 v[76:77], 0
	v_mov_b64_e32 v[78:79], 0
	v_mov_b64_e32 v[80:81], 0
	v_mov_b64_e32 v[82:83], 0
	v_mov_b64_e32 v[84:85], 0
	v_mov_b64_e32 v[86:87], 0
	v_mov_b64_e32 v[88:89], 0
	v_mov_b64_e32 v[90:91], 0
	v_mov_b64_e32 v[92:93], 0
	v_mov_b64_e32 v[94:95], 0
	v_mov_b64_e32 v[96:97], 0
	v_mov_b64_e32 v[98:99], 0
	v_mov_b64_e32 v[100:101], 0
	v_mov_b64_e32 v[102:103], 0
	v_mov_b64_e32 v[104:105], 0
	v_mov_b64_e32 v[106:107], 0
	v_mov_b64_e32 v[108:109], 0
	v_mov_b64_e32 v[110:111], 0
	v_mov_b64_e32 v[112:113], 0
	v_mov_b64_e32 v[114:115], 0
	v_mov_b64_e32 v[116:117], 0
	v_mov_b64_e32 v[118:119], 0
	v_mov_b64_e32 v[120:121], 0
	v_mov_b64_e32 v[122:123], 0
	v_mov_b64_e32 v[124:125], 0
	v_mov_b64_e32 v[126:127], 0

.LBB0_2800:
	s_ashr_i32 s27, s26, 31
	s_lshl_b64 s[4:5], s[26:27], 19
	s_add_u32 s38, s96, s4
	s_addc_u32 s39, s97, s5
	s_and_b64 s[4:5], s[10:11], exec
	s_cselect_b32 s4, s39, s45
	s_cselect_b32 s5, s38, s44
	s_ashr_i32 s25, s24, 31
	s_lshl_b64 s[40:41], s[24:25], 19
	s_add_u32 s40, s66, s40
	s_addc_u32 s41, s67, s41
	s_and_b64 s[48:49], s[10:11], exec
	s_cselect_b32 s25, s41, s47
	s_cselect_b32 s27, s40, s46
	s_add_u32 s66, s46, 0x100
	v_mov_b32_e32 v0, 0
	s_addc_u32 s67, s47, 0
	s_mov_b32 s68, -2
	v_mov_b32_e32 v1, 0
	v_mov_b64_e32 v[2:3], 0
	v_mov_b64_e32 v[4:5], 0
	v_mov_b64_e32 v[6:7], 0
	v_mov_b64_e32 v[8:9], 0
	v_mov_b64_e32 v[10:11], 0
	v_mov_b64_e32 v[12:13], 0
	v_mov_b64_e32 v[14:15], 0
	v_mov_b64_e32 v[16:17], 0
	v_mov_b64_e32 v[18:19], 0
	v_mov_b64_e32 v[20:21], 0
	v_mov_b64_e32 v[22:23], 0
	v_mov_b64_e32 v[24:25], 0
	v_mov_b64_e32 v[26:27], 0
	v_mov_b64_e32 v[28:29], 0
	v_mov_b64_e32 v[30:31], 0
	v_mov_b64_e32 v[32:33], 0
	v_mov_b64_e32 v[34:35], 0
	v_mov_b64_e32 v[36:37], 0
	v_mov_b64_e32 v[38:39], 0
	v_mov_b64_e32 v[40:41], 0
	v_mov_b64_e32 v[42:43], 0
	v_mov_b64_e32 v[44:45], 0
	v_mov_b64_e32 v[46:47], 0
	v_mov_b64_e32 v[48:49], 0
	v_mov_b64_e32 v[50:51], 0
	v_mov_b64_e32 v[52:53], 0
	v_mov_b64_e32 v[54:55], 0
	v_mov_b64_e32 v[56:57], 0
	v_mov_b64_e32 v[58:59], 0
	v_mov_b64_e32 v[60:61], 0
	v_mov_b64_e32 v[62:63], 0
	v_mov_b64_e32 v[64:65], 0
	v_mov_b64_e32 v[66:67], 0
	v_mov_b64_e32 v[68:69], 0
	v_mov_b64_e32 v[70:71], 0
	v_mov_b64_e32 v[72:73], 0
	v_mov_b64_e32 v[74:75], 0
	v_mov_b64_e32 v[76:77], 0
	v_mov_b64_e32 v[78:79], 0
	v_mov_b64_e32 v[80:81], 0
	v_mov_b64_e32 v[82:83], 0
	v_mov_b64_e32 v[84:85], 0
	v_mov_b64_e32 v[86:87], 0
	v_mov_b64_e32 v[88:89], 0
	v_mov_b64_e32 v[90:91], 0
	v_mov_b64_e32 v[92:93], 0
	v_mov_b64_e32 v[94:95], 0
	v_mov_b64_e32 v[96:97], 0
	v_mov_b64_e32 v[98:99], 0
	v_mov_b64_e32 v[100:101], 0
	v_mov_b64_e32 v[102:103], 0
	v_mov_b64_e32 v[104:105], 0
	v_mov_b64_e32 v[106:107], 0
	v_mov_b64_e32 v[108:109], 0
	v_mov_b64_e32 v[110:111], 0
	v_mov_b64_e32 v[112:113], 0
	v_mov_b64_e32 v[114:115], 0
	v_mov_b64_e32 v[116:117], 0
	v_mov_b64_e32 v[118:119], 0
	v_mov_b64_e32 v[120:121], 0
	v_mov_b64_e32 v[122:123], 0
	s_waitcnt vmcnt(0)
	v_mov_b32_e32 v124, v0
	v_mov_b32_e32 v125, v0
	v_mov_b32_e32 v126, v0
	v_mov_b32_e32 v127, v0

.LBB0_2948:
	s_ashr_i32 s17, s16, 31
	s_lshl_b64 s[4:5], s[16:17], 19
	s_add_u32 s18, s96, s4
	s_addc_u32 s19, s97, s5
	s_and_b64 s[4:5], s[8:9], exec
	s_cselect_b32 s4, s19, s25
	s_cselect_b32 s5, s18, s24
	s_ashr_i32 s15, s14, 31
	s_lshl_b64 s[20:21], s[14:15], 19
	v_readlane_b32 s36, v255, 33
	v_readlane_b32 s37, v255, 34
	s_add_u32 s20, s36, s20
	s_addc_u32 s21, s37, s21
	s_and_b64 s[36:37], s[8:9], exec
	s_cselect_b32 s15, s21, s27
	s_cselect_b32 s17, s20, s26
	s_add_u32 s24, s24, 0x40080
	s_addc_u32 s25, s25, 0
	s_add_u32 s51, s26, 0x100
	v_mov_b32_e32 v0, 0
	s_addc_u32 s52, s27, 0
	s_mov_b32 s53, -2
	v_mov_b32_e32 v1, 0
	v_mov_b64_e32 v[2:3], 0
	v_mov_b64_e32 v[4:5], 0
	v_mov_b64_e32 v[6:7], 0
	v_mov_b64_e32 v[8:9], 0
	v_mov_b64_e32 v[10:11], 0
	v_mov_b64_e32 v[12:13], 0
	v_mov_b64_e32 v[14:15], 0
	v_mov_b64_e32 v[16:17], 0
	v_mov_b64_e32 v[18:19], 0
	v_mov_b64_e32 v[20:21], 0
	v_mov_b64_e32 v[22:23], 0
	v_mov_b64_e32 v[24:25], 0
	v_mov_b64_e32 v[26:27], 0
	v_mov_b64_e32 v[28:29], 0
	v_mov_b64_e32 v[30:31], 0
	v_mov_b64_e32 v[32:33], 0
	v_mov_b64_e32 v[34:35], 0
	v_mov_b64_e32 v[36:37], 0
	v_mov_b64_e32 v[38:39], 0
	v_mov_b64_e32 v[40:41], 0
	v_mov_b64_e32 v[42:43], 0
	v_mov_b64_e32 v[44:45], 0
	v_mov_b64_e32 v[46:47], 0
	v_mov_b64_e32 v[48:49], 0
	v_mov_b64_e32 v[50:51], 0
	v_mov_b64_e32 v[52:53], 0
	v_mov_b64_e32 v[54:55], 0
	v_mov_b64_e32 v[56:57], 0
	v_mov_b64_e32 v[58:59], 0
	v_mov_b64_e32 v[60:61], 0
	v_mov_b64_e32 v[62:63], 0
	v_mov_b64_e32 v[64:65], 0
	v_mov_b64_e32 v[66:67], 0
	v_mov_b64_e32 v[68:69], 0
	v_mov_b64_e32 v[70:71], 0
	v_mov_b64_e32 v[72:73], 0
	v_mov_b64_e32 v[74:75], 0
	v_mov_b64_e32 v[76:77], 0
	v_mov_b64_e32 v[78:79], 0
	v_mov_b64_e32 v[80:81], 0
	v_mov_b64_e32 v[82:83], 0
	v_mov_b64_e32 v[84:85], 0
	v_mov_b64_e32 v[86:87], 0
	v_mov_b64_e32 v[88:89], 0
	v_mov_b64_e32 v[90:91], 0
	v_mov_b64_e32 v[92:93], 0
	v_mov_b64_e32 v[94:95], 0
	v_mov_b64_e32 v[96:97], 0
	v_mov_b64_e32 v[98:99], 0
	v_mov_b64_e32 v[100:101], 0
	v_mov_b64_e32 v[102:103], 0
	v_mov_b64_e32 v[104:105], 0
	v_mov_b64_e32 v[106:107], 0
	v_mov_b64_e32 v[108:109], 0
	v_mov_b64_e32 v[110:111], 0
	v_mov_b64_e32 v[112:113], 0
	v_mov_b64_e32 v[114:115], 0
	v_mov_b64_e32 v[116:117], 0
	v_mov_b64_e32 v[118:119], 0
	v_mov_b64_e32 v[120:121], 0
	v_mov_b64_e32 v[122:123], 0
	v_mov_b64_e32 v[124:125], 0
	v_mov_b64_e32 v[126:127], 0

.LBB0_3028:
	s_add_u32 s4, s34, 0x100
	v_mov_b32_e32 v0, 0
	s_addc_u32 s5, s35, 0
	s_mov_b32 s64, -2
	v_mov_b32_e32 v1, 0
	v_mov_b64_e32 v[2:3], 0
	v_mov_b64_e32 v[4:5], 0
	v_mov_b64_e32 v[6:7], 0
	v_mov_b64_e32 v[8:9], 0
	v_mov_b64_e32 v[10:11], 0
	v_mov_b64_e32 v[12:13], 0
	v_mov_b64_e32 v[14:15], 0
	v_mov_b64_e32 v[16:17], 0
	v_mov_b64_e32 v[18:19], 0
	v_mov_b64_e32 v[20:21], 0
	v_mov_b64_e32 v[22:23], 0
	v_mov_b64_e32 v[24:25], 0
	v_mov_b64_e32 v[26:27], 0
	v_mov_b64_e32 v[28:29], 0
	v_mov_b64_e32 v[30:31], 0
	v_mov_b64_e32 v[32:33], 0
	v_mov_b64_e32 v[34:35], 0
	v_mov_b64_e32 v[36:37], 0
	v_mov_b64_e32 v[38:39], 0
	v_mov_b64_e32 v[40:41], 0
	v_mov_b64_e32 v[42:43], 0
	v_mov_b64_e32 v[44:45], 0
	v_mov_b64_e32 v[46:47], 0
	v_mov_b64_e32 v[48:49], 0
	v_mov_b64_e32 v[50:51], 0
	v_mov_b64_e32 v[52:53], 0
	v_mov_b64_e32 v[54:55], 0
	v_mov_b64_e32 v[56:57], 0
	v_mov_b64_e32 v[58:59], 0
	v_mov_b64_e32 v[60:61], 0
	v_mov_b64_e32 v[62:63], 0
	v_mov_b64_e32 v[64:65], 0
	v_mov_b64_e32 v[66:67], 0
	v_mov_b64_e32 v[68:69], 0
	v_mov_b64_e32 v[70:71], 0
	v_mov_b64_e32 v[72:73], 0
	v_mov_b64_e32 v[74:75], 0
	v_mov_b64_e32 v[76:77], 0
	v_mov_b64_e32 v[78:79], 0
	v_mov_b64_e32 v[80:81], 0
	v_mov_b64_e32 v[82:83], 0
	v_mov_b64_e32 v[84:85], 0
	v_mov_b64_e32 v[86:87], 0
	v_mov_b64_e32 v[88:89], 0
	v_mov_b64_e32 v[90:91], 0
	v_mov_b64_e32 v[92:93], 0
	v_mov_b64_e32 v[94:95], 0
	v_mov_b64_e32 v[96:97], 0
	v_mov_b64_e32 v[98:99], 0
	v_mov_b64_e32 v[100:101], 0
	v_mov_b64_e32 v[102:103], 0
	v_mov_b64_e32 v[104:105], 0
	v_mov_b64_e32 v[106:107], 0
	v_mov_b64_e32 v[108:109], 0
	v_mov_b64_e32 v[110:111], 0
	v_mov_b64_e32 v[112:113], 0
	v_mov_b64_e32 v[114:115], 0
	v_mov_b64_e32 v[116:117], 0
	v_mov_b64_e32 v[118:119], 0
	v_mov_b64_e32 v[120:121], 0
	v_mov_b64_e32 v[122:123], 0
	v_mov_b64_e32 v[124:125], 0
	v_mov_b64_e32 v[126:127], 0

.LBB0_3178:
	s_ashr_i32 s25, s24, 31
	s_lshl_b64 s[4:5], s[24:25], 19
	s_add_u32 s26, s96, s4
	s_addc_u32 s27, s97, s5
	s_and_b64 s[4:5], s[8:9], exec
	s_cselect_b32 s4, s27, s15
	s_cselect_b32 s5, s26, s14
	s_ashr_i32 s23, s22, 31
	s_lshl_b64 s[30:31], s[22:23], 19
	v_readlane_b32 s36, v255, 15
	v_readlane_b32 s37, v255, 16
	s_add_u32 s30, s36, s30
	s_addc_u32 s31, s37, s31
	s_and_b64 s[36:37], s[8:9], exec
	s_cselect_b32 s11, s31, s35
	s_cselect_b32 s13, s30, s34
	s_add_u32 s14, s14, 0x40080
	s_addc_u32 s15, s15, 0
	s_add_u32 s23, s34, 0x100
	v_mov_b32_e32 v0, 0
	s_addc_u32 s25, s35, 0
	s_mov_b32 s54, -2
	v_mov_b32_e32 v1, 0
	v_mov_b64_e32 v[2:3], 0
	v_mov_b64_e32 v[4:5], 0
	v_mov_b64_e32 v[6:7], 0
	v_mov_b64_e32 v[8:9], 0
	v_mov_b64_e32 v[10:11], 0
	v_mov_b64_e32 v[12:13], 0
	v_mov_b64_e32 v[14:15], 0
	v_mov_b64_e32 v[16:17], 0
	v_mov_b64_e32 v[18:19], 0
	v_mov_b64_e32 v[20:21], 0
	v_mov_b64_e32 v[22:23], 0
	v_mov_b64_e32 v[24:25], 0
	v_mov_b64_e32 v[26:27], 0
	v_mov_b64_e32 v[28:29], 0
	v_mov_b64_e32 v[30:31], 0
	v_mov_b64_e32 v[32:33], 0
	v_mov_b64_e32 v[34:35], 0
	v_mov_b64_e32 v[36:37], 0
	v_mov_b64_e32 v[38:39], 0
	v_mov_b64_e32 v[40:41], 0
	v_mov_b64_e32 v[42:43], 0
	v_mov_b64_e32 v[44:45], 0
	v_mov_b64_e32 v[46:47], 0
	v_mov_b64_e32 v[48:49], 0
	v_mov_b64_e32 v[50:51], 0
	v_mov_b64_e32 v[52:53], 0
	v_mov_b64_e32 v[54:55], 0
	v_mov_b64_e32 v[56:57], 0
	v_mov_b64_e32 v[58:59], 0
	v_mov_b64_e32 v[60:61], 0
	v_mov_b64_e32 v[62:63], 0
	v_mov_b64_e32 v[64:65], 0
	v_mov_b64_e32 v[66:67], 0
	v_mov_b64_e32 v[68:69], 0
	v_mov_b64_e32 v[70:71], 0
	v_mov_b64_e32 v[72:73], 0
	v_mov_b64_e32 v[74:75], 0
	v_mov_b64_e32 v[76:77], 0
	v_mov_b64_e32 v[78:79], 0
	v_mov_b64_e32 v[80:81], 0
	v_mov_b64_e32 v[82:83], 0
	v_mov_b64_e32 v[84:85], 0
	v_mov_b64_e32 v[86:87], 0
	v_mov_b64_e32 v[88:89], 0
	v_mov_b64_e32 v[90:91], 0
	v_mov_b64_e32 v[92:93], 0
	v_mov_b64_e32 v[94:95], 0
	v_mov_b64_e32 v[96:97], 0
	v_mov_b64_e32 v[98:99], 0
	v_mov_b64_e32 v[100:101], 0
	v_mov_b64_e32 v[102:103], 0
	v_mov_b64_e32 v[104:105], 0
	v_mov_b64_e32 v[106:107], 0
	v_mov_b64_e32 v[108:109], 0
	v_mov_b64_e32 v[110:111], 0
	v_mov_b64_e32 v[112:113], 0
	v_mov_b64_e32 v[114:115], 0
	v_mov_b64_e32 v[116:117], 0
	v_mov_b64_e32 v[118:119], 0
	v_mov_b64_e32 v[120:121], 0
	v_mov_b64_e32 v[122:123], 0
	v_mov_b64_e32 v[124:125], 0
	v_mov_b64_e32 v[126:127], 0

.LBB0_3533:
	s_ashr_i32 s23, s22, 31
	s_lshl_b64 s[4:5], s[22:23], 19
	s_add_u32 s24, s96, s4
	s_addc_u32 s25, s97, s5
	s_and_b64 s[4:5], s[6:7], exec
	s_cselect_b32 s4, s25, s31
	s_cselect_b32 s5, s24, s30
	s_ashr_i32 s21, s20, 31
	s_lshl_b64 s[26:27], s[20:21], 19
	v_readlane_b32 s36, v254, 38
	v_readlane_b32 s37, v254, 39
	s_add_u32 s26, s36, s26
	s_addc_u32 s27, s37, s27
	s_and_b64 s[36:37], s[6:7], exec
	s_cselect_b32 s21, s27, s35
	s_cselect_b32 s23, s26, s34
	s_add_u32 s66, s34, 0x100
	v_mov_b32_e32 v0, 0
	s_addc_u32 s67, s35, 0
	s_mov_b32 s68, -2
	v_mov_b32_e32 v1, 0
	v_mov_b64_e32 v[2:3], 0
	v_mov_b64_e32 v[4:5], 0
	v_mov_b64_e32 v[6:7], 0
	v_mov_b64_e32 v[8:9], 0
	v_mov_b64_e32 v[10:11], 0
	v_mov_b64_e32 v[12:13], 0
	v_mov_b64_e32 v[14:15], 0
	v_mov_b64_e32 v[16:17], 0
	v_mov_b64_e32 v[18:19], 0
	v_mov_b64_e32 v[20:21], 0
	v_mov_b64_e32 v[22:23], 0
	v_mov_b64_e32 v[24:25], 0
	v_mov_b64_e32 v[26:27], 0
	v_mov_b64_e32 v[28:29], 0
	v_mov_b64_e32 v[30:31], 0
	v_mov_b64_e32 v[32:33], 0
	v_mov_b64_e32 v[34:35], 0
	v_mov_b64_e32 v[36:37], 0
	v_mov_b64_e32 v[38:39], 0
	v_mov_b64_e32 v[40:41], 0
	v_mov_b64_e32 v[42:43], 0
	v_mov_b64_e32 v[44:45], 0
	v_mov_b64_e32 v[46:47], 0
	v_mov_b64_e32 v[48:49], 0
	v_mov_b64_e32 v[50:51], 0
	v_mov_b64_e32 v[52:53], 0
	v_mov_b64_e32 v[54:55], 0
	v_mov_b64_e32 v[56:57], 0
	v_mov_b64_e32 v[58:59], 0
	v_mov_b64_e32 v[60:61], 0
	v_mov_b64_e32 v[62:63], 0
	v_mov_b64_e32 v[64:65], 0
	v_mov_b64_e32 v[66:67], 0
	v_mov_b64_e32 v[68:69], 0
	v_mov_b64_e32 v[70:71], 0
	v_mov_b64_e32 v[72:73], 0
	v_mov_b64_e32 v[74:75], 0
	v_mov_b64_e32 v[76:77], 0
	v_mov_b64_e32 v[78:79], 0
	v_mov_b64_e32 v[80:81], 0
	v_mov_b64_e32 v[82:83], 0
	v_mov_b64_e32 v[84:85], 0
	v_mov_b64_e32 v[86:87], 0
	v_mov_b64_e32 v[88:89], 0
	v_mov_b64_e32 v[90:91], 0
	v_mov_b64_e32 v[92:93], 0
	v_mov_b64_e32 v[94:95], 0
	v_mov_b64_e32 v[96:97], 0
	v_mov_b64_e32 v[98:99], 0
	v_mov_b64_e32 v[100:101], 0
	v_mov_b64_e32 v[102:103], 0
	v_mov_b64_e32 v[104:105], 0
	v_mov_b64_e32 v[106:107], 0
	v_mov_b64_e32 v[108:109], 0
	v_mov_b64_e32 v[110:111], 0
	v_mov_b64_e32 v[112:113], 0
	v_mov_b64_e32 v[114:115], 0
	v_mov_b64_e32 v[116:117], 0
	v_mov_b64_e32 v[118:119], 0
	v_mov_b64_e32 v[120:121], 0
	v_mov_b64_e32 v[122:123], 0
	v_mov_b64_e32 v[124:125], 0
	v_mov_b64_e32 v[126:127], 0

.LBB0_3662:
	s_ashr_i32 s15, s14, 31
	s_lshl_b64 s[4:5], s[14:15], 19
	s_add_u32 s16, s96, s4
	s_addc_u32 s17, s97, s5
	s_and_b64 s[4:5], s[6:7], exec
	s_cselect_b32 s4, s17, s23
	s_cselect_b32 s5, s16, s22
	s_ashr_i32 s13, s12, 31
	s_lshl_b64 s[18:19], s[12:13], 19
	v_readlane_b32 s26, v254, 41
	v_readlane_b32 s27, v254, 42
	s_add_u32 s18, s26, s18
	s_addc_u32 s19, s27, s19
	s_and_b64 s[26:27], s[6:7], exec
	s_cselect_b32 s13, s19, s25
	s_cselect_b32 s15, s18, s24
	s_add_u32 s22, s22, 0x40080
	s_addc_u32 s23, s23, 0
	s_add_u32 s51, s24, 0x100
	v_mov_b32_e32 v0, 0
	s_addc_u32 s52, s25, 0
	s_mov_b32 s53, -2
	v_mov_b32_e32 v1, 0
	v_mov_b64_e32 v[2:3], 0
	v_mov_b64_e32 v[4:5], 0
	v_mov_b64_e32 v[6:7], 0
	v_mov_b64_e32 v[8:9], 0
	v_mov_b64_e32 v[10:11], 0
	v_mov_b64_e32 v[12:13], 0
	v_mov_b64_e32 v[14:15], 0
	v_mov_b64_e32 v[16:17], 0
	v_mov_b64_e32 v[18:19], 0
	v_mov_b64_e32 v[20:21], 0
	v_mov_b64_e32 v[22:23], 0
	v_mov_b64_e32 v[24:25], 0
	v_mov_b64_e32 v[26:27], 0
	v_mov_b64_e32 v[28:29], 0
	v_mov_b64_e32 v[30:31], 0
	v_mov_b64_e32 v[32:33], 0
	v_mov_b64_e32 v[34:35], 0
	v_mov_b64_e32 v[36:37], 0
	v_mov_b64_e32 v[38:39], 0
	v_mov_b64_e32 v[40:41], 0
	v_mov_b64_e32 v[42:43], 0
	v_mov_b64_e32 v[44:45], 0
	v_mov_b64_e32 v[46:47], 0
	v_mov_b64_e32 v[48:49], 0
	v_mov_b64_e32 v[50:51], 0
	v_mov_b64_e32 v[52:53], 0
	v_mov_b64_e32 v[54:55], 0
	v_mov_b64_e32 v[56:57], 0
	v_mov_b64_e32 v[58:59], 0
	v_mov_b64_e32 v[60:61], 0
	v_mov_b64_e32 v[62:63], 0
	v_mov_b64_e32 v[64:65], 0
	v_mov_b64_e32 v[66:67], 0
	v_mov_b64_e32 v[68:69], 0
	v_mov_b64_e32 v[70:71], 0
	v_mov_b64_e32 v[72:73], 0
	v_mov_b64_e32 v[74:75], 0
	v_mov_b64_e32 v[76:77], 0
	v_mov_b64_e32 v[78:79], 0
	v_mov_b64_e32 v[80:81], 0
	v_mov_b64_e32 v[82:83], 0
	v_mov_b64_e32 v[84:85], 0
	v_mov_b64_e32 v[86:87], 0
	v_mov_b64_e32 v[88:89], 0
	v_mov_b64_e32 v[90:91], 0
	v_mov_b64_e32 v[92:93], 0
	v_mov_b64_e32 v[94:95], 0
	v_mov_b64_e32 v[96:97], 0
	v_mov_b64_e32 v[98:99], 0
	v_mov_b64_e32 v[100:101], 0
	v_mov_b64_e32 v[102:103], 0
	v_mov_b64_e32 v[104:105], 0
	v_mov_b64_e32 v[106:107], 0
	v_mov_b64_e32 v[108:109], 0
	v_mov_b64_e32 v[110:111], 0
	v_mov_b64_e32 v[112:113], 0
	v_mov_b64_e32 v[114:115], 0
	v_mov_b64_e32 v[116:117], 0
	v_mov_b64_e32 v[118:119], 0
	v_mov_b64_e32 v[120:121], 0
	v_mov_b64_e32 v[122:123], 0
	v_mov_b64_e32 v[124:125], 0
	v_mov_b64_e32 v[126:127], 0

.LBB0_3742:
	s_add_u32 s58, s26, 0x100
	v_mov_b32_e32 v0, 0
	s_addc_u32 s59, s27, 0
	s_mov_b32 s60, -2
	v_mov_b32_e32 v1, 0
	v_mov_b64_e32 v[2:3], 0
	v_mov_b64_e32 v[4:5], 0
	v_mov_b64_e32 v[6:7], 0
	v_mov_b64_e32 v[8:9], 0
	v_mov_b64_e32 v[10:11], 0
	v_mov_b64_e32 v[12:13], 0
	v_mov_b64_e32 v[14:15], 0
	v_mov_b64_e32 v[16:17], 0
	v_mov_b64_e32 v[18:19], 0
	v_mov_b64_e32 v[20:21], 0
	v_mov_b64_e32 v[22:23], 0
	v_mov_b64_e32 v[24:25], 0
	v_mov_b64_e32 v[26:27], 0
	v_mov_b64_e32 v[28:29], 0
	v_mov_b64_e32 v[30:31], 0
	v_mov_b64_e32 v[32:33], 0
	v_mov_b64_e32 v[34:35], 0
	v_mov_b64_e32 v[36:37], 0
	v_mov_b64_e32 v[38:39], 0
	v_mov_b64_e32 v[40:41], 0
	v_mov_b64_e32 v[42:43], 0
	v_mov_b64_e32 v[44:45], 0
	v_mov_b64_e32 v[46:47], 0
	v_mov_b64_e32 v[48:49], 0
	v_mov_b64_e32 v[50:51], 0
	v_mov_b64_e32 v[52:53], 0
	v_mov_b64_e32 v[54:55], 0
	v_mov_b64_e32 v[56:57], 0
	v_mov_b64_e32 v[58:59], 0
	v_mov_b64_e32 v[60:61], 0
	v_mov_b64_e32 v[62:63], 0
	v_mov_b64_e32 v[64:65], 0
	v_mov_b64_e32 v[66:67], 0
	v_mov_b64_e32 v[68:69], 0
	v_mov_b64_e32 v[70:71], 0
	v_mov_b64_e32 v[72:73], 0
	v_mov_b64_e32 v[74:75], 0
	v_mov_b64_e32 v[76:77], 0
	v_mov_b64_e32 v[78:79], 0
	v_mov_b64_e32 v[80:81], 0
	v_mov_b64_e32 v[82:83], 0
	v_mov_b64_e32 v[84:85], 0
	v_mov_b64_e32 v[86:87], 0
	v_mov_b64_e32 v[88:89], 0
	v_mov_b64_e32 v[90:91], 0
	v_mov_b64_e32 v[92:93], 0
	v_mov_b64_e32 v[94:95], 0
	v_mov_b64_e32 v[96:97], 0
	v_mov_b64_e32 v[98:99], 0
	v_mov_b64_e32 v[100:101], 0
	v_mov_b64_e32 v[102:103], 0
	v_mov_b64_e32 v[104:105], 0
	v_mov_b64_e32 v[106:107], 0
	v_mov_b64_e32 v[108:109], 0
	v_mov_b64_e32 v[110:111], 0
	v_mov_b64_e32 v[112:113], 0
	v_mov_b64_e32 v[114:115], 0
	v_mov_b64_e32 v[116:117], 0
	v_mov_b64_e32 v[118:119], 0
	v_mov_b64_e32 v[120:121], 0
	v_mov_b64_e32 v[122:123], 0
	v_mov_b64_e32 v[124:125], 0
	v_mov_b64_e32 v[126:127], 0
